# nt hint on the fused epilogue's residual loads
# baseline (speedup 1.0000x reference)
.LBB0_1169:
	ds_read_b128 v[128:131], v167
	ds_read_b128 v[132:135], v167 offset:1024
	ds_read_b128 v[136:139], v167 offset:2048
	ds_read_b128 v[156:159], v167 offset:3072
	s_add_u32 s6, s40, 0x100
	s_addc_u32 s7, s41, 0
	s_cmp_eq_u32 s65, 40
	s_cselect_b32 s45, s1, s7
	s_cselect_b32 s44, s0, s6
	s_cselect_b32 s43, s39, s64
	s_cselect_b32 s42, s38, s63
	v_lshl_add_u64 v[202:203], s[40:41], 0, v[148:149]
	s_add_i32 m0, s47, 0xc000
	ds_read_b128 v[160:163], v168
	ds_read_b128 v[172:175], v168 offset:1024
	ds_read_b128 v[176:179], v168 offset:2048
	ds_read_b128 v[180:183], v168 offset:3072
	ds_read_b128 v[184:187], v168 offset:4096
	ds_read_b128 v[188:191], v168 offset:5120
	ds_read_b128 v[194:197], v168 offset:6144
	ds_read_b128 v[198:201], v168 offset:7168
	global_load_lds_dwordx4 v[202:203], off
	v_lshl_add_u64 v[202:203], s[40:41], 0, v[150:151]
	s_add_i32 m0, s47, 0xe000
	s_nop 0
	global_load_lds_dwordx4 v[202:203], off
	s_waitcnt lgkmcnt(8)
	s_barrier
	s_waitcnt lgkmcnt(0)
	s_setprio 1
	s_waitcnt lgkmcnt(0)
	v_mfma_f32_16x16x32_bf16 v[124:127], v[128:131], v[160:163], v[124:127]
	v_mfma_f32_16x16x32_bf16 v[120:123], v[136:139], v[160:163], v[120:123]
	v_mfma_f32_16x16x32_bf16 v[108:111], v[128:131], v[176:179], v[108:111]
	v_mfma_f32_16x16x32_bf16 v[104:107], v[136:139], v[176:179], v[104:107]
	v_mfma_f32_16x16x32_bf16 v[92:95], v[128:131], v[184:187], v[92:95]
	v_mfma_f32_16x16x32_bf16 v[88:91], v[136:139], v[184:187], v[88:91]
	v_mfma_f32_16x16x32_bf16 v[76:79], v[128:131], v[194:197], v[76:79]
	v_mfma_f32_16x16x32_bf16 v[72:75], v[136:139], v[194:197], v[72:75]
	v_mfma_f32_16x16x32_bf16 v[124:127], v[132:135], v[172:175], v[124:127]
	v_mfma_f32_16x16x32_bf16 v[120:123], v[156:159], v[172:175], v[120:123]
	v_mfma_f32_16x16x32_bf16 v[108:111], v[132:135], v[180:183], v[108:111]
	v_mfma_f32_16x16x32_bf16 v[104:107], v[156:159], v[180:183], v[104:107]
	v_mfma_f32_16x16x32_bf16 v[92:95], v[132:135], v[188:191], v[92:95]
	v_mfma_f32_16x16x32_bf16 v[88:91], v[156:159], v[188:191], v[88:91]
	v_mfma_f32_16x16x32_bf16 v[76:79], v[132:135], v[198:201], v[76:79]
	v_mfma_f32_16x16x32_bf16 v[72:75], v[156:159], v[198:201], v[72:75]
	s_setprio 0
	s_barrier
	s_add_i32 s28, s57, s46
	v_lshl_add_u64 v[218:219], s[42:43], 0, v[142:143]
	s_mov_b32 m0, s28
	ds_read_b128 v[202:205], v169
	ds_read_b128 v[206:209], v169 offset:1024
	ds_read_b128 v[210:213], v169 offset:2048
	ds_read_b128 v[214:217], v169 offset:3072
	global_load_lds_dwordx4 v[218:219], off
	v_lshl_add_u64 v[220:221], s[42:43], 0, v[146:147]
	s_add_i32 m0, s28, 0x2000
	s_nop 0
	global_load_lds_dwordx4 v[220:221], off
	s_barrier
	s_waitcnt lgkmcnt(0)
	s_setprio 1
	s_waitcnt lgkmcnt(0)
	v_mfma_f32_16x16x32_bf16 v[116:119], v[202:205], v[160:163], v[116:119]
	v_mfma_f32_16x16x32_bf16 v[112:115], v[210:213], v[160:163], v[112:115]
	v_mfma_f32_16x16x32_bf16 v[100:103], v[202:205], v[176:179], v[100:103]
	v_mfma_f32_16x16x32_bf16 v[96:99], v[210:213], v[176:179], v[96:99]
	v_mfma_f32_16x16x32_bf16 v[84:87], v[202:205], v[184:187], v[84:87]
	v_mfma_f32_16x16x32_bf16 v[80:83], v[210:213], v[184:187], v[80:83]
	v_mfma_f32_16x16x32_bf16 v[68:71], v[202:205], v[194:197], v[68:71]
	v_mfma_f32_16x16x32_bf16 v[64:67], v[210:213], v[194:197], v[64:67]
	v_mfma_f32_16x16x32_bf16 v[116:119], v[206:209], v[172:175], v[116:119]
	v_mfma_f32_16x16x32_bf16 v[112:115], v[214:217], v[172:175], v[112:115]
	v_mfma_f32_16x16x32_bf16 v[100:103], v[206:209], v[180:183], v[100:103]
	v_mfma_f32_16x16x32_bf16 v[96:99], v[214:217], v[180:183], v[96:99]
	v_mfma_f32_16x16x32_bf16 v[84:87], v[206:209], v[188:191], v[84:87]
	v_mfma_f32_16x16x32_bf16 v[80:83], v[214:217], v[188:191], v[80:83]
	v_mfma_f32_16x16x32_bf16 v[68:71], v[206:209], v[198:201], v[68:71]
	v_mfma_f32_16x16x32_bf16 v[64:67], v[214:217], v[198:201], v[64:67]
	s_setprio 0
	s_mov_b32 m0, s47
	v_lshl_add_u64 v[222:223], s[44:45], 0, v[140:141]
	s_barrier
	ds_read_b128 v[160:163], v168 offset:16384
	ds_read_b128 v[172:175], v168 offset:17408
	ds_read_b128 v[176:179], v168 offset:18432
	ds_read_b128 v[180:183], v168 offset:19456
	ds_read_b128 v[184:187], v168 offset:20480
	ds_read_b128 v[188:191], v168 offset:21504
	ds_read_b128 v[194:197], v168 offset:22528
	ds_read_b128 v[198:201], v168 offset:23552
	global_load_lds_dwordx4 v[222:223], off
	v_lshl_add_u64 v[224:225], s[44:45], 0, v[144:145]
	s_mov_b32 m0, s48
	s_nop 0
	global_load_lds_dwordx4 v[224:225], off
	s_barrier
	s_waitcnt lgkmcnt(0)
	s_setprio 1
	s_waitcnt lgkmcnt(0)
	v_mfma_f32_16x16x32_bf16 v[60:63], v[128:131], v[160:163], v[60:63]
	v_mfma_f32_16x16x32_bf16 v[56:59], v[136:139], v[160:163], v[56:59]
	v_mfma_f32_16x16x32_bf16 v[44:47], v[128:131], v[176:179], v[44:47]
	v_mfma_f32_16x16x32_bf16 v[40:43], v[136:139], v[176:179], v[40:43]
	v_mfma_f32_16x16x32_bf16 v[28:31], v[128:131], v[184:187], v[28:31]
	v_mfma_f32_16x16x32_bf16 v[24:27], v[136:139], v[184:187], v[24:27]
	v_mfma_f32_16x16x32_bf16 v[12:15], v[128:131], v[194:197], v[12:15]
	v_mfma_f32_16x16x32_bf16 v[8:11], v[136:139], v[194:197], v[8:11]
	v_mfma_f32_16x16x32_bf16 v[60:63], v[132:135], v[172:175], v[60:63]
	v_mfma_f32_16x16x32_bf16 v[56:59], v[156:159], v[172:175], v[56:59]
	v_mfma_f32_16x16x32_bf16 v[44:47], v[132:135], v[180:183], v[44:47]
	v_mfma_f32_16x16x32_bf16 v[40:43], v[156:159], v[180:183], v[40:43]
	v_mfma_f32_16x16x32_bf16 v[28:31], v[132:135], v[188:191], v[28:31]
	v_mfma_f32_16x16x32_bf16 v[24:27], v[156:159], v[188:191], v[24:27]
	v_mfma_f32_16x16x32_bf16 v[12:15], v[132:135], v[198:201], v[12:15]
	v_mfma_f32_16x16x32_bf16 v[8:11], v[156:159], v[198:201], v[8:11]
	s_setprio 0
	s_barrier
	s_add_u32 s40, s42, 0x2c000
	s_addc_u32 s41, s43, 0
	s_add_i32 s28, s58, s46
	v_lshl_add_u64 v[128:129], s[40:41], 0, v[142:143]
	s_mov_b32 m0, s28
	s_nop 0
	global_load_lds_dwordx4 v[128:129], off
	v_lshl_add_u64 v[128:129], s[40:41], 0, v[146:147]
	s_add_i32 m0, s28, 0x2000
	s_nop 0
	global_load_lds_dwordx4 v[128:129], off
	s_waitcnt vmcnt(6)
	s_barrier
	s_setprio 1
	v_mfma_f32_16x16x32_bf16 v[52:55], v[202:205], v[160:163], v[52:55]
	v_mfma_f32_16x16x32_bf16 v[48:51], v[210:213], v[160:163], v[48:51]
	v_mfma_f32_16x16x32_bf16 v[36:39], v[202:205], v[176:179], v[36:39]
	v_mfma_f32_16x16x32_bf16 v[32:35], v[210:213], v[176:179], v[32:35]
	v_mfma_f32_16x16x32_bf16 v[20:23], v[202:205], v[184:187], v[20:23]
	v_mfma_f32_16x16x32_bf16 v[16:19], v[210:213], v[184:187], v[16:19]
	v_mfma_f32_16x16x32_bf16 v[4:7], v[202:205], v[194:197], v[4:7]
	v_mfma_f32_16x16x32_bf16 v[0:3], v[210:213], v[194:197], v[0:3]
	v_mfma_f32_16x16x32_bf16 v[52:55], v[206:209], v[172:175], v[52:55]
	v_mfma_f32_16x16x32_bf16 v[48:51], v[214:217], v[172:175], v[48:51]
	v_mfma_f32_16x16x32_bf16 v[36:39], v[206:209], v[180:183], v[36:39]
	v_mfma_f32_16x16x32_bf16 v[32:35], v[214:217], v[180:183], v[32:35]
	v_mfma_f32_16x16x32_bf16 v[20:23], v[206:209], v[188:191], v[20:23]
	v_mfma_f32_16x16x32_bf16 v[16:19], v[214:217], v[188:191], v[16:19]
	v_mfma_f32_16x16x32_bf16 v[4:7], v[206:209], v[198:201], v[4:7]
	v_mfma_f32_16x16x32_bf16 v[0:3], v[214:217], v[198:201], v[0:3]
	s_setprio 0
	s_add_i32 s28, 0, 0x18000
	v_add_u32_e32 v156, s28, v165
	s_barrier
	ds_read_b128 v[128:131], v156
	ds_read_b128 v[132:135], v156 offset:1024
	ds_read_b128 v[136:139], v156 offset:2048
	ds_read_b128 v[156:159], v156 offset:3072
	s_add_u32 s40, s44, 0xb0000
	s_addc_u32 s41, s45, 0
	s_mov_b32 m0, s49
	v_lshl_add_u64 v[202:203], s[40:41], 0, v[140:141]
	ds_read_b128 v[160:163], v168 offset:32768
	ds_read_b128 v[172:175], v168 offset:33792
	ds_read_b128 v[176:179], v168 offset:34816
	ds_read_b128 v[180:183], v168 offset:35840
	ds_read_b128 v[184:187], v168 offset:36864
	ds_read_b128 v[188:191], v168 offset:37888
	ds_read_b128 v[194:197], v168 offset:38912
	ds_read_b128 v[198:201], v168 offset:39936
	global_load_lds_dwordx4 v[202:203], off
	v_lshl_add_u64 v[202:203], s[40:41], 0, v[144:145]
	s_mov_b32 m0, s50
	s_nop 0
	global_load_lds_dwordx4 v[202:203], off
	s_waitcnt lgkmcnt(8)
	s_barrier
	s_waitcnt lgkmcnt(0)
	s_setprio 1
	s_waitcnt lgkmcnt(0)
	v_mfma_f32_16x16x32_bf16 v[124:127], v[128:131], v[160:163], v[124:127]
	v_mfma_f32_16x16x32_bf16 v[120:123], v[136:139], v[160:163], v[120:123]
	v_mfma_f32_16x16x32_bf16 v[108:111], v[128:131], v[176:179], v[108:111]
	v_mfma_f32_16x16x32_bf16 v[104:107], v[136:139], v[176:179], v[104:107]
	v_mfma_f32_16x16x32_bf16 v[92:95], v[128:131], v[184:187], v[92:95]
	v_mfma_f32_16x16x32_bf16 v[88:91], v[136:139], v[184:187], v[88:91]
	v_mfma_f32_16x16x32_bf16 v[76:79], v[128:131], v[194:197], v[76:79]
	v_mfma_f32_16x16x32_bf16 v[72:75], v[136:139], v[194:197], v[72:75]
	v_mfma_f32_16x16x32_bf16 v[124:127], v[132:135], v[172:175], v[124:127]
	v_mfma_f32_16x16x32_bf16 v[120:123], v[156:159], v[172:175], v[120:123]
	v_mfma_f32_16x16x32_bf16 v[108:111], v[132:135], v[180:183], v[108:111]
	v_mfma_f32_16x16x32_bf16 v[104:107], v[156:159], v[180:183], v[104:107]
	v_mfma_f32_16x16x32_bf16 v[92:95], v[132:135], v[188:191], v[92:95]
	v_mfma_f32_16x16x32_bf16 v[88:91], v[156:159], v[188:191], v[88:91]
	v_mfma_f32_16x16x32_bf16 v[76:79], v[132:135], v[198:201], v[76:79]
	v_mfma_f32_16x16x32_bf16 v[72:75], v[156:159], v[198:201], v[72:75]
	s_setprio 0
	s_barrier
	s_add_i32 s29, 0, 0x1c000
	s_add_i32 s28, s28, s46
	v_add_u32_e32 v171, s29, v165
	v_lshl_add_u64 v[218:219], v[218:219], 0, s[36:37]
	s_mov_b32 m0, s28
	ds_read_b128 v[202:205], v171
	ds_read_b128 v[206:209], v171 offset:1024
	ds_read_b128 v[210:213], v171 offset:2048
	ds_read_b128 v[214:217], v171 offset:3072
	global_load_lds_dwordx4 v[218:219], off
	v_lshl_add_u64 v[218:219], v[220:221], 0, s[36:37]
	s_add_i32 m0, s28, 0x2000
	s_nop 0
	global_load_lds_dwordx4 v[218:219], off
	s_barrier
	s_waitcnt lgkmcnt(0)
	s_setprio 1
	s_waitcnt lgkmcnt(0)
	v_mfma_f32_16x16x32_bf16 v[116:119], v[202:205], v[160:163], v[116:119]
	v_mfma_f32_16x16x32_bf16 v[112:115], v[210:213], v[160:163], v[112:115]
	v_mfma_f32_16x16x32_bf16 v[100:103], v[202:205], v[176:179], v[100:103]
	v_mfma_f32_16x16x32_bf16 v[96:99], v[210:213], v[176:179], v[96:99]
	v_mfma_f32_16x16x32_bf16 v[84:87], v[202:205], v[184:187], v[84:87]
	v_mfma_f32_16x16x32_bf16 v[80:83], v[210:213], v[184:187], v[80:83]
	v_mfma_f32_16x16x32_bf16 v[68:71], v[202:205], v[194:197], v[68:71]
	v_mfma_f32_16x16x32_bf16 v[64:67], v[210:213], v[194:197], v[64:67]
	v_mfma_f32_16x16x32_bf16 v[116:119], v[206:209], v[172:175], v[116:119]
	v_mfma_f32_16x16x32_bf16 v[112:115], v[214:217], v[172:175], v[112:115]
	v_mfma_f32_16x16x32_bf16 v[100:103], v[206:209], v[180:183], v[100:103]
	v_mfma_f32_16x16x32_bf16 v[96:99], v[214:217], v[180:183], v[96:99]
	v_mfma_f32_16x16x32_bf16 v[84:87], v[206:209], v[188:191], v[84:87]
	v_mfma_f32_16x16x32_bf16 v[80:83], v[214:217], v[188:191], v[80:83]
	v_mfma_f32_16x16x32_bf16 v[68:71], v[206:209], v[198:201], v[68:71]
	v_mfma_f32_16x16x32_bf16 v[64:67], v[214:217], v[198:201], v[64:67]
	s_setprio 0
	s_mov_b32 m0, s54
	v_lshl_add_u64 v[218:219], v[222:223], 0, s[36:37]
	s_barrier
	ds_read_b128 v[160:163], v168 offset:49152
	ds_read_b128 v[172:175], v168 offset:50176
	ds_read_b128 v[176:179], v168 offset:51200
	ds_read_b128 v[180:183], v168 offset:52224
	ds_read_b128 v[184:187], v168 offset:53248
	ds_read_b128 v[188:191], v168 offset:54272
	ds_read_b128 v[194:197], v168 offset:55296
	ds_read_b128 v[198:201], v168 offset:56320
	global_load_lds_dwordx4 v[218:219], off
	v_lshl_add_u64 v[218:219], v[224:225], 0, s[36:37]
	s_mov_b32 m0, s55
	s_nop 0
	global_load_lds_dwordx4 v[218:219], off
	s_barrier
	s_waitcnt lgkmcnt(0)
	s_setprio 1
	s_waitcnt lgkmcnt(0)
	v_mfma_f32_16x16x32_bf16 v[60:63], v[128:131], v[160:163], v[60:63]
	v_mfma_f32_16x16x32_bf16 v[56:59], v[136:139], v[160:163], v[56:59]
	v_mfma_f32_16x16x32_bf16 v[44:47], v[128:131], v[176:179], v[44:47]
	v_mfma_f32_16x16x32_bf16 v[40:43], v[136:139], v[176:179], v[40:43]
	v_mfma_f32_16x16x32_bf16 v[28:31], v[128:131], v[184:187], v[28:31]
	v_mfma_f32_16x16x32_bf16 v[24:27], v[136:139], v[184:187], v[24:27]
	v_mfma_f32_16x16x32_bf16 v[12:15], v[128:131], v[194:197], v[12:15]
	v_mfma_f32_16x16x32_bf16 v[8:11], v[136:139], v[194:197], v[8:11]
	v_mfma_f32_16x16x32_bf16 v[60:63], v[132:135], v[172:175], v[60:63]
	v_mfma_f32_16x16x32_bf16 v[56:59], v[156:159], v[172:175], v[56:59]
	v_mfma_f32_16x16x32_bf16 v[44:47], v[132:135], v[180:183], v[44:47]
	v_mfma_f32_16x16x32_bf16 v[40:43], v[156:159], v[180:183], v[40:43]
	v_mfma_f32_16x16x32_bf16 v[28:31], v[132:135], v[188:191], v[28:31]
	v_mfma_f32_16x16x32_bf16 v[24:27], v[156:159], v[188:191], v[24:27]
	v_mfma_f32_16x16x32_bf16 v[12:15], v[132:135], v[198:201], v[12:15]
	v_mfma_f32_16x16x32_bf16 v[8:11], v[156:159], v[198:201], v[8:11]
	s_setprio 0
	s_barrier
	s_add_u32 s40, s42, 0x2c080
	s_addc_u32 s41, s43, 0
	s_add_i32 s28, s29, s46
	v_lshl_add_u64 v[128:129], s[40:41], 0, v[142:143]
	s_mov_b32 m0, s28
	s_nop 0
	global_load_lds_dwordx4 v[128:129], off
	v_lshl_add_u64 v[128:129], s[40:41], 0, v[146:147]
	s_add_i32 m0, s28, 0x2000
	s_nop 0
	global_load_lds_dwordx4 v[128:129], off
	s_waitcnt vmcnt(6)
	s_barrier
	s_setprio 1
	v_mfma_f32_16x16x32_bf16 v[52:55], v[202:205], v[160:163], v[52:55]
	v_mfma_f32_16x16x32_bf16 v[48:51], v[210:213], v[160:163], v[48:51]
	v_mfma_f32_16x16x32_bf16 v[36:39], v[202:205], v[176:179], v[36:39]
	v_mfma_f32_16x16x32_bf16 v[32:35], v[210:213], v[176:179], v[32:35]
	v_mfma_f32_16x16x32_bf16 v[20:23], v[202:205], v[184:187], v[20:23]
	v_mfma_f32_16x16x32_bf16 v[16:19], v[210:213], v[184:187], v[16:19]
	v_mfma_f32_16x16x32_bf16 v[4:7], v[202:205], v[194:197], v[4:7]
	v_mfma_f32_16x16x32_bf16 v[0:3], v[210:213], v[194:197], v[0:3]
	v_mfma_f32_16x16x32_bf16 v[52:55], v[206:209], v[172:175], v[52:55]
	v_mfma_f32_16x16x32_bf16 v[48:51], v[214:217], v[172:175], v[48:51]
	v_mfma_f32_16x16x32_bf16 v[36:39], v[206:209], v[180:183], v[36:39]
	v_mfma_f32_16x16x32_bf16 v[32:35], v[214:217], v[180:183], v[32:35]
	v_mfma_f32_16x16x32_bf16 v[20:23], v[206:209], v[188:191], v[20:23]
	v_mfma_f32_16x16x32_bf16 v[16:19], v[214:217], v[188:191], v[16:19]
	v_mfma_f32_16x16x32_bf16 v[4:7], v[206:209], v[198:201], v[4:7]
	v_mfma_f32_16x16x32_bf16 v[0:3], v[214:217], v[198:201], v[0:3]
	s_setprio 0
	s_add_i32 s65, s65, 2
	s_add_u32 s63, s63, 0x100
	s_addc_u32 s64, s64, 0
	s_cmp_gt_u32 s65, 41
	s_mov_b64 s[40:41], s[6:7]
	s_barrier
	s_cbranch_scc0 .LBB0_1169
	v_lshl_add_u32 v171, s62, 8, v164
	v_lshl_or_b32 v188, s10, 8, v166
	s_mov_b32 s63, 0xffff0000
	v_lshlrev_b32_e32 v128, 11, v171
	v_lshl_add_u32 v128, v188, 1, v128
	v_lshlrev_b32_e32 v129, 12, v171
	v_lshl_add_u32 v129, v188, 2, v129
	v_lshlrev_b32_e32 v132, 2, v188
	s_mov_b64 s[70:71], s[68:69]
	global_load_dwordx4 v[194:197], v128, s[70:71] nt
	global_load_dwordx4 v[198:201], v128, s[70:71] offset:64 nt
	s_add_u32 s70, s70, 0x8000
	s_addc_u32 s71, s71, 0
	global_load_dwordx4 v[202:205], v128, s[70:71] nt
	global_load_dwordx4 v[206:209], v128, s[70:71] offset:64 nt
	s_add_u32 s70, s70, 0x8000
	s_addc_u32 s71, s71, 0
	global_load_dwordx4 v[210:213], v128, s[70:71] nt
	global_load_dwordx4 v[214:217], v128, s[70:71] offset:64 nt
	s_add_u32 s70, s70, 0x8000
	s_addc_u32 s71, s71, 0
	global_load_dwordx4 v[218:221], v128, s[70:71] nt
	global_load_dwordx4 v[222:225], v128, s[70:71] offset:64 nt
	s_add_u32 s70, s70, 0x28000
	s_addc_u32 s71, s71, 0
	global_load_dwordx4 v[226:229], v128, s[70:71] nt
	global_load_dwordx4 v[230:233], v128, s[70:71] offset:64 nt
	s_add_u32 s70, s70, 0x8000
	s_addc_u32 s71, s71, 0
	global_load_dwordx4 v[234:237], v128, s[70:71] nt
	global_load_dwordx4 v[238:241], v128, s[70:71] offset:64 nt
	s_add_u32 s70, s70, 0x8000
	s_addc_u32 s71, s71, 0
	global_load_dwordx4 v[172:175], v128, s[70:71] nt
	global_load_dwordx4 v[176:179], v128, s[70:71] offset:64 nt
	s_add_u32 s70, s70, 0x8000
	s_addc_u32 s71, s71, 0
	global_load_dwordx4 v[180:183], v128, s[70:71] nt
	global_load_dwordx4 v[184:187], v128, s[70:71] offset:64 nt
	s_bfe_u32 s42, s17, 0x20006
	s_lshl_b32 s43, s10, 4
	s_lshl_b32 s42, s42, 2
	s_add_i32 s43, s43, s42
	v_lshl_add_u32 v130, v171, 6, s43
	v_and_b32_e32 v131, 48, v170
	v_lshl_add_u32 v131, v171, 6, v131
	v_xor_b32_e32 v134, 16, v170
	v_xor_b32_e32 v135, 32, v170
	v_lshlrev_b32_e32 v134, 2, v134
	v_lshlrev_b32_e32 v135, 2, v135
	v_cmp_gt_u32_e64 s[64:65], 16, v170
	s_add_u32 s74, s8, 0x2000
	s_addc_u32 s75, s9, 0
	s_lshl_b32 s42, s62, 7
	s_add_u32 s78, s26, 0x3c08000
	s_addc_u32 s79, s27, 0
	s_add_u32 s78, s78, s42
	s_addc_u32 s79, s79, 0
	s_waitcnt vmcnt(14)
	v_lshlrev_b32_e32 v136, 16, v194
	v_and_b32_e32 v137, s63, v194
	v_pk_add_f32 v[124:125], v[124:125], v[136:137]
	v_lshlrev_b32_e32 v138, 16, v195
	v_and_b32_e32 v139, s63, v195
	v_pk_add_f32 v[126:127], v[126:127], v[138:139]
	v_lshlrev_b32_e32 v190, 16, v196
	v_and_b32_e32 v191, s63, v196
	v_pk_add_f32 v[120:121], v[120:121], v[190:191]
	v_lshlrev_b32_e32 v136, 16, v197
	v_and_b32_e32 v137, s63, v197
	v_pk_add_f32 v[122:123], v[122:123], v[136:137]
	v_lshlrev_b32_e32 v138, 16, v198
	v_and_b32_e32 v139, s63, v198
	v_pk_add_f32 v[116:117], v[116:117], v[138:139]
	v_lshlrev_b32_e32 v190, 16, v199
	v_and_b32_e32 v191, s63, v199
	v_pk_add_f32 v[118:119], v[118:119], v[190:191]
	v_lshlrev_b32_e32 v136, 16, v200
	v_and_b32_e32 v137, s63, v200
	v_pk_add_f32 v[112:113], v[112:113], v[136:137]
	v_lshlrev_b32_e32 v138, 16, v201
	v_and_b32_e32 v139, s63, v201
	v_pk_add_f32 v[114:115], v[114:115], v[138:139]
	v_mul_f32_e32 v156, v120, v120
	v_mul_f32_e32 v189, v112, v112
	v_fmac_f32_e32 v156, v121, v121
	v_fmac_f32_e32 v189, v113, v113
	v_fmac_f32_e32 v156, v122, v122
	v_fmac_f32_e32 v189, v114, v114
	v_fmac_f32_e32 v156, v123, v123
	v_fmac_f32_e32 v189, v115, v115
	v_fmac_f32_e32 v156, v124, v124
	v_fmac_f32_e32 v189, v116, v116
	v_fmac_f32_e32 v156, v125, v125
	v_fmac_f32_e32 v189, v117, v117
	v_fmac_f32_e32 v156, v126, v126
	v_fmac_f32_e32 v189, v118, v118
	v_fmac_f32_e32 v156, v127, v127
	v_fmac_f32_e32 v189, v119, v119
	v_add_f32_e32 v156, v156, v189
	s_waitcnt vmcnt(12)
	v_lshlrev_b32_e32 v190, 16, v202
	v_and_b32_e32 v191, s63, v202
	v_pk_add_f32 v[108:109], v[108:109], v[190:191]
	v_lshlrev_b32_e32 v136, 16, v203
	v_and_b32_e32 v137, s63, v203
	v_pk_add_f32 v[110:111], v[110:111], v[136:137]
	v_lshlrev_b32_e32 v138, 16, v204
	v_and_b32_e32 v139, s63, v204
	v_pk_add_f32 v[104:105], v[104:105], v[138:139]
	v_lshlrev_b32_e32 v190, 16, v205
	v_and_b32_e32 v191, s63, v205
	v_pk_add_f32 v[106:107], v[106:107], v[190:191]
	v_lshlrev_b32_e32 v136, 16, v206
	v_and_b32_e32 v137, s63, v206
	v_pk_add_f32 v[100:101], v[100:101], v[136:137]
	v_lshlrev_b32_e32 v138, 16, v207
	v_and_b32_e32 v139, s63, v207
	v_pk_add_f32 v[102:103], v[102:103], v[138:139]
	v_lshlrev_b32_e32 v190, 16, v208
	v_and_b32_e32 v191, s63, v208
	v_pk_add_f32 v[96:97], v[96:97], v[190:191]
	v_lshlrev_b32_e32 v136, 16, v209
	v_and_b32_e32 v137, s63, v209
	v_pk_add_f32 v[98:99], v[98:99], v[136:137]
	v_mul_f32_e32 v157, v104, v104
	v_mul_f32_e32 v189, v96, v96
	v_fmac_f32_e32 v157, v105, v105
	v_fmac_f32_e32 v189, v97, v97
	v_fmac_f32_e32 v157, v106, v106
	v_fmac_f32_e32 v189, v98, v98
	v_fmac_f32_e32 v157, v107, v107
	v_fmac_f32_e32 v189, v99, v99
	v_fmac_f32_e32 v157, v108, v108
	v_fmac_f32_e32 v189, v100, v100
	v_fmac_f32_e32 v157, v109, v109
	v_fmac_f32_e32 v189, v101, v101
	v_fmac_f32_e32 v157, v110, v110
	v_fmac_f32_e32 v189, v102, v102
	v_fmac_f32_e32 v157, v111, v111
	v_fmac_f32_e32 v189, v103, v103
	v_add_f32_e32 v157, v157, v189
	s_waitcnt vmcnt(10)
	v_lshlrev_b32_e32 v138, 16, v210
	v_and_b32_e32 v139, s63, v210
	v_pk_add_f32 v[92:93], v[92:93], v[138:139]
	v_lshlrev_b32_e32 v190, 16, v211
	v_and_b32_e32 v191, s63, v211
	v_pk_add_f32 v[94:95], v[94:95], v[190:191]
	v_lshlrev_b32_e32 v136, 16, v212
	v_and_b32_e32 v137, s63, v212
	v_pk_add_f32 v[88:89], v[88:89], v[136:137]
	v_lshlrev_b32_e32 v138, 16, v213
	v_and_b32_e32 v139, s63, v213
	v_pk_add_f32 v[90:91], v[90:91], v[138:139]
	v_lshlrev_b32_e32 v190, 16, v214
	v_and_b32_e32 v191, s63, v214
	v_pk_add_f32 v[84:85], v[84:85], v[190:191]
	v_lshlrev_b32_e32 v136, 16, v215
	v_and_b32_e32 v137, s63, v215
	v_pk_add_f32 v[86:87], v[86:87], v[136:137]
	v_lshlrev_b32_e32 v138, 16, v216
	v_and_b32_e32 v139, s63, v216
	v_pk_add_f32 v[80:81], v[80:81], v[138:139]
	v_lshlrev_b32_e32 v190, 16, v217
	v_and_b32_e32 v191, s63, v217
	v_pk_add_f32 v[82:83], v[82:83], v[190:191]
	v_mul_f32_e32 v158, v88, v88
	v_mul_f32_e32 v189, v80, v80
	v_fmac_f32_e32 v158, v89, v89
	v_fmac_f32_e32 v189, v81, v81
	v_fmac_f32_e32 v158, v90, v90
	v_fmac_f32_e32 v189, v82, v82
	v_fmac_f32_e32 v158, v91, v91
	v_fmac_f32_e32 v189, v83, v83
	v_fmac_f32_e32 v158, v92, v92
	v_fmac_f32_e32 v189, v84, v84
	v_fmac_f32_e32 v158, v93, v93
	v_fmac_f32_e32 v189, v85, v85
	v_fmac_f32_e32 v158, v94, v94
	v_fmac_f32_e32 v189, v86, v86
	v_fmac_f32_e32 v158, v95, v95
	v_fmac_f32_e32 v189, v87, v87
	v_add_f32_e32 v158, v158, v189
	s_waitcnt vmcnt(8)
	v_lshlrev_b32_e32 v136, 16, v218
	v_and_b32_e32 v137, s63, v218
	v_pk_add_f32 v[76:77], v[76:77], v[136:137]
	v_lshlrev_b32_e32 v138, 16, v219
	v_and_b32_e32 v139, s63, v219
	v_pk_add_f32 v[78:79], v[78:79], v[138:139]
	v_lshlrev_b32_e32 v190, 16, v220
	v_and_b32_e32 v191, s63, v220
	v_pk_add_f32 v[72:73], v[72:73], v[190:191]
	v_lshlrev_b32_e32 v136, 16, v221
	v_and_b32_e32 v137, s63, v221
	v_pk_add_f32 v[74:75], v[74:75], v[136:137]
	v_lshlrev_b32_e32 v138, 16, v222
	v_and_b32_e32 v139, s63, v222
	v_pk_add_f32 v[68:69], v[68:69], v[138:139]
	v_lshlrev_b32_e32 v190, 16, v223
	v_and_b32_e32 v191, s63, v223
	v_pk_add_f32 v[70:71], v[70:71], v[190:191]
	v_lshlrev_b32_e32 v136, 16, v224
	v_and_b32_e32 v137, s63, v224
	v_pk_add_f32 v[64:65], v[64:65], v[136:137]
	v_lshlrev_b32_e32 v138, 16, v225
	v_and_b32_e32 v139, s63, v225
	v_pk_add_f32 v[66:67], v[66:67], v[138:139]
	v_mul_f32_e32 v159, v72, v72
	v_mul_f32_e32 v189, v64, v64
	v_fmac_f32_e32 v159, v73, v73
	v_fmac_f32_e32 v189, v65, v65
	v_fmac_f32_e32 v159, v74, v74
	v_fmac_f32_e32 v189, v66, v66
	v_fmac_f32_e32 v159, v75, v75
	v_fmac_f32_e32 v189, v67, v67
	v_fmac_f32_e32 v159, v76, v76
	v_fmac_f32_e32 v189, v68, v68
	v_fmac_f32_e32 v159, v77, v77
	v_fmac_f32_e32 v189, v69, v69
	v_fmac_f32_e32 v159, v78, v78
	v_fmac_f32_e32 v189, v70, v70
	v_fmac_f32_e32 v159, v79, v79
	v_fmac_f32_e32 v189, v71, v71
	v_add_f32_e32 v159, v159, v189
	s_waitcnt vmcnt(6)
	v_lshlrev_b32_e32 v190, 16, v226
	v_and_b32_e32 v191, s63, v226
	v_pk_add_f32 v[60:61], v[60:61], v[190:191]
	v_lshlrev_b32_e32 v136, 16, v227
	v_and_b32_e32 v137, s63, v227
	v_pk_add_f32 v[62:63], v[62:63], v[136:137]
	v_lshlrev_b32_e32 v138, 16, v228
	v_and_b32_e32 v139, s63, v228
	v_pk_add_f32 v[56:57], v[56:57], v[138:139]
	v_lshlrev_b32_e32 v190, 16, v229
	v_and_b32_e32 v191, s63, v229
	v_pk_add_f32 v[58:59], v[58:59], v[190:191]
	v_lshlrev_b32_e32 v136, 16, v230
	v_and_b32_e32 v137, s63, v230
	v_pk_add_f32 v[52:53], v[52:53], v[136:137]
	v_lshlrev_b32_e32 v138, 16, v231
	v_and_b32_e32 v139, s63, v231
	v_pk_add_f32 v[54:55], v[54:55], v[138:139]
	v_lshlrev_b32_e32 v190, 16, v232
	v_and_b32_e32 v191, s63, v232
	v_pk_add_f32 v[48:49], v[48:49], v[190:191]
	v_lshlrev_b32_e32 v136, 16, v233
	v_and_b32_e32 v137, s63, v233
	v_pk_add_f32 v[50:51], v[50:51], v[136:137]
	v_mul_f32_e32 v160, v56, v56
	v_mul_f32_e32 v189, v48, v48
	v_fmac_f32_e32 v160, v57, v57
	v_fmac_f32_e32 v189, v49, v49
	v_fmac_f32_e32 v160, v58, v58
	v_fmac_f32_e32 v189, v50, v50
	v_fmac_f32_e32 v160, v59, v59
	v_fmac_f32_e32 v189, v51, v51
	v_fmac_f32_e32 v160, v60, v60
	v_fmac_f32_e32 v189, v52, v52
	v_fmac_f32_e32 v160, v61, v61
	v_fmac_f32_e32 v189, v53, v53
	v_fmac_f32_e32 v160, v62, v62
	v_fmac_f32_e32 v189, v54, v54
	v_fmac_f32_e32 v160, v63, v63
	v_fmac_f32_e32 v189, v55, v55
	v_add_f32_e32 v160, v160, v189
	s_waitcnt vmcnt(4)
	v_lshlrev_b32_e32 v138, 16, v234
	v_and_b32_e32 v139, s63, v234
	v_pk_add_f32 v[44:45], v[44:45], v[138:139]
	v_lshlrev_b32_e32 v190, 16, v235
	v_and_b32_e32 v191, s63, v235
	v_pk_add_f32 v[46:47], v[46:47], v[190:191]
	v_lshlrev_b32_e32 v136, 16, v236
	v_and_b32_e32 v137, s63, v236
	v_pk_add_f32 v[40:41], v[40:41], v[136:137]
	v_lshlrev_b32_e32 v138, 16, v237
	v_and_b32_e32 v139, s63, v237
	v_pk_add_f32 v[42:43], v[42:43], v[138:139]
	v_lshlrev_b32_e32 v190, 16, v238
	v_and_b32_e32 v191, s63, v238
	v_pk_add_f32 v[36:37], v[36:37], v[190:191]
	v_lshlrev_b32_e32 v136, 16, v239
	v_and_b32_e32 v137, s63, v239
	v_pk_add_f32 v[38:39], v[38:39], v[136:137]
	v_lshlrev_b32_e32 v138, 16, v240
	v_and_b32_e32 v139, s63, v240
	v_pk_add_f32 v[32:33], v[32:33], v[138:139]
	v_lshlrev_b32_e32 v190, 16, v241
	v_and_b32_e32 v191, s63, v241
	v_pk_add_f32 v[34:35], v[34:35], v[190:191]
	v_mul_f32_e32 v161, v40, v40
	v_mul_f32_e32 v189, v32, v32
	v_fmac_f32_e32 v161, v41, v41
	v_fmac_f32_e32 v189, v33, v33
	v_fmac_f32_e32 v161, v42, v42
	v_fmac_f32_e32 v189, v34, v34
	v_fmac_f32_e32 v161, v43, v43
	v_fmac_f32_e32 v189, v35, v35
	v_fmac_f32_e32 v161, v44, v44
	v_fmac_f32_e32 v189, v36, v36
	v_fmac_f32_e32 v161, v45, v45
	v_fmac_f32_e32 v189, v37, v37
	v_fmac_f32_e32 v161, v46, v46
	v_fmac_f32_e32 v189, v38, v38
	v_fmac_f32_e32 v161, v47, v47
	v_fmac_f32_e32 v189, v39, v39
	v_add_f32_e32 v161, v161, v189
	s_waitcnt vmcnt(2)
	v_lshlrev_b32_e32 v136, 16, v172
	v_and_b32_e32 v137, s63, v172
	v_pk_add_f32 v[28:29], v[28:29], v[136:137]
	v_lshlrev_b32_e32 v138, 16, v173
	v_and_b32_e32 v139, s63, v173
	v_pk_add_f32 v[30:31], v[30:31], v[138:139]
	v_lshlrev_b32_e32 v190, 16, v174
	v_and_b32_e32 v191, s63, v174
	v_pk_add_f32 v[24:25], v[24:25], v[190:191]
	v_lshlrev_b32_e32 v136, 16, v175
	v_and_b32_e32 v137, s63, v175
	v_pk_add_f32 v[26:27], v[26:27], v[136:137]
	v_lshlrev_b32_e32 v138, 16, v176
	v_and_b32_e32 v139, s63, v176
	v_pk_add_f32 v[20:21], v[20:21], v[138:139]
	v_lshlrev_b32_e32 v190, 16, v177
	v_and_b32_e32 v191, s63, v177
	v_pk_add_f32 v[22:23], v[22:23], v[190:191]
	v_lshlrev_b32_e32 v136, 16, v178
	v_and_b32_e32 v137, s63, v178
	v_pk_add_f32 v[16:17], v[16:17], v[136:137]
	v_lshlrev_b32_e32 v138, 16, v179
	v_and_b32_e32 v139, s63, v179
	v_pk_add_f32 v[18:19], v[18:19], v[138:139]
	v_mul_f32_e32 v162, v24, v24
	v_mul_f32_e32 v189, v16, v16
	v_fmac_f32_e32 v162, v25, v25
	v_fmac_f32_e32 v189, v17, v17
	v_fmac_f32_e32 v162, v26, v26
	v_fmac_f32_e32 v189, v18, v18
	v_fmac_f32_e32 v162, v27, v27
	v_fmac_f32_e32 v189, v19, v19
	v_fmac_f32_e32 v162, v28, v28
	v_fmac_f32_e32 v189, v20, v20
	v_fmac_f32_e32 v162, v29, v29
	v_fmac_f32_e32 v189, v21, v21
	v_fmac_f32_e32 v162, v30, v30
	v_fmac_f32_e32 v189, v22, v22
	v_fmac_f32_e32 v162, v31, v31
	v_fmac_f32_e32 v189, v23, v23
	v_add_f32_e32 v162, v162, v189
	s_waitcnt vmcnt(0)
	v_lshlrev_b32_e32 v190, 16, v180
	v_and_b32_e32 v191, s63, v180
	v_pk_add_f32 v[12:13], v[12:13], v[190:191]
	v_lshlrev_b32_e32 v136, 16, v181
	v_and_b32_e32 v137, s63, v181
	v_pk_add_f32 v[14:15], v[14:15], v[136:137]
	v_lshlrev_b32_e32 v138, 16, v182
	v_and_b32_e32 v139, s63, v182
	v_pk_add_f32 v[8:9], v[8:9], v[138:139]
	v_lshlrev_b32_e32 v190, 16, v183
	v_and_b32_e32 v191, s63, v183
	v_pk_add_f32 v[10:11], v[10:11], v[190:191]
	v_lshlrev_b32_e32 v136, 16, v184
	v_and_b32_e32 v137, s63, v184
	v_pk_add_f32 v[4:5], v[4:5], v[136:137]
	v_lshlrev_b32_e32 v138, 16, v185
	v_and_b32_e32 v139, s63, v185
	v_pk_add_f32 v[6:7], v[6:7], v[138:139]
	v_lshlrev_b32_e32 v190, 16, v186
	v_and_b32_e32 v191, s63, v186
	v_pk_add_f32 v[0:1], v[0:1], v[190:191]
	v_lshlrev_b32_e32 v136, 16, v187
	v_and_b32_e32 v137, s63, v187
	v_pk_add_f32 v[2:3], v[2:3], v[136:137]
	v_mul_f32_e32 v163, v8, v8
	v_mul_f32_e32 v189, v0, v0
	v_fmac_f32_e32 v163, v9, v9
	v_fmac_f32_e32 v189, v1, v1
	v_fmac_f32_e32 v163, v10, v10
	v_fmac_f32_e32 v189, v2, v2
	v_fmac_f32_e32 v163, v11, v11
	v_fmac_f32_e32 v189, v3, v3
	v_fmac_f32_e32 v163, v12, v12
	v_fmac_f32_e32 v189, v4, v4
	v_fmac_f32_e32 v163, v13, v13
	v_fmac_f32_e32 v189, v5, v5
	v_fmac_f32_e32 v163, v14, v14
	v_fmac_f32_e32 v189, v6, v6
	v_fmac_f32_e32 v163, v15, v15
	v_fmac_f32_e32 v189, v7, v7
	v_add_f32_e32 v163, v163, v189
	ds_bpermute_b32 v136, v134, v156
	ds_bpermute_b32 v137, v134, v157
	ds_bpermute_b32 v138, v134, v158
	ds_bpermute_b32 v139, v134, v159
	ds_bpermute_b32 v188, v134, v160
	ds_bpermute_b32 v189, v134, v161
	ds_bpermute_b32 v190, v134, v162
	ds_bpermute_b32 v191, v134, v163
	s_waitcnt lgkmcnt(0)
	v_add_f32_e32 v156, v156, v136
	v_add_f32_e32 v157, v157, v137
	v_add_f32_e32 v158, v158, v138
	v_add_f32_e32 v159, v159, v139
	v_add_f32_e32 v160, v160, v188
	v_add_f32_e32 v161, v161, v189
	v_add_f32_e32 v162, v162, v190
	v_add_f32_e32 v163, v163, v191
	ds_bpermute_b32 v136, v135, v156
	ds_bpermute_b32 v137, v135, v157
	ds_bpermute_b32 v138, v135, v158
	ds_bpermute_b32 v139, v135, v159
	ds_bpermute_b32 v188, v135, v160
	ds_bpermute_b32 v189, v135, v161
	ds_bpermute_b32 v190, v135, v162
	ds_bpermute_b32 v191, v135, v163
	s_waitcnt lgkmcnt(0)
	v_add_f32_e32 v156, v156, v136
	v_add_f32_e32 v157, v157, v137
	v_add_f32_e32 v158, v158, v138
	v_add_f32_e32 v159, v159, v139
	v_add_f32_e32 v160, v160, v188
	v_add_f32_e32 v161, v161, v189
	v_add_f32_e32 v162, v162, v190
	v_add_f32_e32 v163, v163, v191
	s_and_saveexec_b64 s[66:67], s[64:65]
	global_store_dword v130, v156, s[8:9] sc1
	global_store_dword v130, v157, s[8:9] offset:1024 sc1
	global_store_dword v130, v158, s[8:9] offset:2048 sc1
	global_store_dword v130, v159, s[8:9] offset:3072 sc1
	global_store_dword v130, v160, s[74:75] sc1
	global_store_dword v130, v161, s[74:75] offset:1024 sc1
	global_store_dword v130, v162, s[74:75] offset:2048 sc1
	global_store_dword v130, v163, s[74:75] offset:3072 sc1
	s_or_b64 exec, exec, s[66:67]
	global_load_dwordx4 v[210:213], v132, s[22:23]
	global_load_dwordx4 v[214:217], v132, s[22:23] offset:16
	global_load_dwordx4 v[218:221], v132, s[22:23] offset:128
	global_load_dwordx4 v[222:225], v132, s[22:23] offset:144
	s_waitcnt vmcnt(0)
	s_barrier
	s_barrier
	s_cmpk_gt_u32 s17, 0xff
	s_cbranch_scc1 .Lf11_w1_a
	s_and_saveexec_b64 s[40:41], s[14:15]
	s_cbranch_execz .Lf11_t0_done
	v_mov_b32_e32 v133, 0
	v_mov_b32_e32 v189, 1
	global_atomic_add v133, v189, s[78:79]
	s_mov_b32 s80, 0
